# last layer: no grid barrier + no separate final phase; each workgroup adds x+delta0+delta1 for its own out-proj tiles (delta1 read back sc1)
# speedup vs baseline: 1.0107x; 1.0035x over previous
; #define PG8_WAIT_V(n) asm volatile("s_waitcnt vmcnt(" #n ")" ::: "memory")
; #define PG8_BAR __builtin_amdgcn_s_barrier()
; #define GSYNC() xcd_barrier(bar)
; template <class Epi, class Sched, bool ALIGN_EPI = false, bool SP2 = false>
; __device__ __forceinline__ void gemm_phase(PG8_LAS unsigned char* lds, const Gemm g, const Sched& S, const Epi& E) {
;     ...
;     PG8_WAIT_V(0);
;     if constexpr (!ALIGN_EPI) { if (wr == 0) PG8_BAR; }
;     PG8_BAR;
; __global__ void __launch_bounds__(NTHR, 2) hymba_fwd(Params Pk) {
;     ...
;         for (int rp = 0; rp < REP_G2L0; ++rp) phase_gemm2(l, lds, G, bx);
;     ...
;         for (int rp = 0; rp < REP_SYNC; ++rp) GSYNC();
;     }
;     phase_final(vcu, G);
.LBB0_685:
	s_waitcnt vmcnt(0)
	s_barrier
	v_readlane_b32 s98, v247, 63
	s_cmp_eq_u32 s98, 0
	s_cbranch_scc1 .Lft_not_last
	s_branch .Lfinal_tiles
.Lft_not_last:
	s_and_saveexec_b64 s[0:1], s[84:85]
	s_cbranch_execnz .LBB0_686
	s_getpc_b64 s[98:99]

;     __host__ __device__ bool next(int i, Unit& u) const {
;         const long L = (long)i * G + c; if (L >= nwg) return false;
;         int wgid = (int)L; { const int q = nwg / NXCD, r = nwg % NXCD, xcd = wgid % NXCD, off = wgid / NXCD; wgid = (xcd < r ? xcd * (q + 1) : r * (q + 1) + (xcd - r) * q) + off; }
;         const int nig = WGM * nN, gid = wgid / nig, fm = gid * WGM, gsz = (nM - fm) < WGM ? (nM - fm) : WGM;
;         u.pm = fm + ((wgid % nig) % gsz); u.pn = (wgid % nig) / gsz; return true;
; __device__ __forceinline__ void phase_final(int vcu, int G) {
;     ...
;     for (unsigned i = (unsigned)vcu * NTHR + tid; i < n8; i += (unsigned)G * NTHR) {
;         const unsigned row = i >> 7, col = (i & 127) * 8;
;         const v4u d = *(const v4u*)(DL + (size_t)i * 8), e = *(const v4u*)(D0 + (size_t)row * DIN + d0_col((int)col));
;         f32x4 a = *(const f32x4*)(xin + (size_t)i * 8), b = *(const f32x4*)(xin + (size_t)i * 8 + 4);
;         a.x += bflo(d.x) + bflo(e.x); a.y += bfhi(d.x) + bfhi(e.x); a.z += bflo(d.y) + bflo(e.y); a.w += bfhi(d.y) + bfhi(e.y);
;         b.x += bflo(d.z) + bflo(e.z); b.y += bfhi(d.z) + bfhi(e.z); b.z += bflo(d.w) + bflo(e.w); b.w += bfhi(d.w) + bfhi(e.w);
;         *(f32x4*)(out + (size_t)i * 8) = a; *(f32x4*)(out + (size_t)i * 8 + 4) = b; }
.Lfinal_tiles:
	s_load_dwordx4 s[4:7], s[90:91], 0xd0
	s_load_dwordx2 s[0:1], s[90:91], 0x0
	v_readlane_b32 s16, v247, 44
	s_mov_b32 s17, 0
	v_mov_b32_e32 v1, 0
	v_mov_b32_e32 v3, 0x380
	v_mov_b32_e32 v4, 0x280
	s_movk_i32 s11, 0x380
	s_movk_i32 s12, 0x17f
	s_waitcnt lgkmcnt(0)
	s_add_u32 s2, s6, 0x15000000
	s_addc_u32 s3, s7, 0
	s_add_u32 s6, s6, 0x6000000
	s_addc_u32 s7, s7, 0
.Lft_tile:
	s_mul_i32 s18, s17, s52
	s_add_u32 s18, s18, s16
	s_cmp_ge_u32 s18, 0x200
	s_cbranch_scc1 .Lft_done
	s_and_b32 s19, s18, 7
	s_lshr_b32 s18, s18, 3
	s_lshl_b32 s19, s19, 6
	s_add_u32 s18, s19, s18
	s_lshr_b32 s19, s18, 5
	s_lshl_b32 s19, s19, 3
	s_and_b32 s20, s18, 7
	s_add_u32 s19, s19, s20
	s_bfe_u32 s20, s18, 0x20003
	s_lshl_b32 s19, s19, 15
	s_lshl_b32 s20, s20, 5
	s_add_u32 s19, s19, s20
	v_lshrrev_b32_e32 v2, 5, v218
	v_lshlrev_b32_e32 v2, 7, v2
	v_and_b32_e32 v5, 31, v218
	v_add3_u32 v2, v2, v5, s19
	v_lshlrev_b32_e32 v0, 3, v2
	s_movk_i32 s22, 16
.Lft_loop:
	v_and_b32_e32 v14, 0x3f8, v0
	v_lshrrev_b32_e32 v5, 7, v2
	v_cmp_gt_u32_e32 vcc, s11, v14
	v_mul_u32_u24_e32 v10, 0xf00, v5
	v_mov_b32_e32 v11, v1
	v_cndmask_b32_e32 v5, v3, v4, vcc
	v_cmp_lt_u32_e32 vcc, s12, v14
	v_lshl_add_u64 v[6:7], v[0:1], 1, s[2:3]
	v_mov_b32_e32 v15, v1
	v_cndmask_b32_e32 v5, 0, v5, vcc
	v_lshlrev_b64 v[22:23], 2, v[0:1]
	v_lshl_add_u64 v[16:17], v[10:11], 1, s[6:7]
	v_add_lshl_u32 v14, v5, v14, 1
	global_load_dwordx4 v[6:9], v[6:7], off sc1
	v_lshl_add_u64 v[24:25], s[0:1], 0, v[22:23]
	v_lshl_add_u64 v[26:27], v[16:17], 0, v[14:15]
	global_load_dwordx4 v[10:13], v[24:25], off
	global_load_dwordx4 v[14:17], v[26:27], off
	global_load_dwordx4 v[18:21], v[24:25], off offset:16
	v_add_u32_e32 v2, 0x800, v2
	v_add_u32_e32 v0, 0x4000, v0
	v_lshl_add_u64 v[22:23], s[4:5], 0, v[22:23]
	s_waitcnt vmcnt(3)
	v_lshlrev_b32_e32 v24, 16, v6
	v_and_b32_e32 v25, 0xffff0000, v6
	v_lshlrev_b32_e32 v6, 16, v7
	v_and_b32_e32 v7, 0xffff0000, v7
	s_waitcnt vmcnt(1)
	v_lshlrev_b32_e32 v28, 16, v14
	v_and_b32_e32 v29, 0xffff0000, v14
	v_lshlrev_b32_e32 v14, 16, v15
	v_and_b32_e32 v15, 0xffff0000, v15
	v_lshlrev_b32_e32 v26, 16, v8
	v_and_b32_e32 v27, 0xffff0000, v8
	v_lshlrev_b32_e32 v8, 16, v9
	v_and_b32_e32 v9, 0xffff0000, v9
	v_lshlrev_b32_e32 v30, 16, v16
	v_and_b32_e32 v31, 0xffff0000, v16
	v_lshlrev_b32_e32 v16, 16, v17
	v_and_b32_e32 v17, 0xffff0000, v17
	v_pk_add_f32 v[24:25], v[24:25], v[28:29]
	v_pk_add_f32 v[14:15], v[6:7], v[14:15]
	v_pk_add_f32 v[26:27], v[26:27], v[30:31]
	v_pk_add_f32 v[16:17], v[8:9], v[16:17]
	v_pk_add_f32 v[6:7], v[10:11], v[24:25]
	v_pk_add_f32 v[8:9], v[12:13], v[14:15]
	s_waitcnt vmcnt(0)
	v_pk_add_f32 v[10:11], v[18:19], v[26:27]
	v_pk_add_f32 v[12:13], v[20:21], v[16:17]
	global_store_dwordx4 v[22:23], v[6:9], off
	global_store_dwordx4 v[22:23], v[10:13], off offset:16
	s_sub_u32 s22, s22, 1
	s_cmp_lg_u32 s22, 0
	s_cbranch_scc1 .Lft_loop
	s_add_u32 s17, s17, 1
	s_branch .Lft_tile
.Lft_done:
	s_endpgm
.LBB0_732:
	v_readlane_b32 s2, v247, 23
	s_mov_b32 s0, 0x400000
	s_nop 0
	v_lshl_add_u32 v2, s2, 9, v218
	v_cmp_gt_u32_e32 vcc, s0, v2
	s_and_saveexec_b64 s[0:1], vcc
	v_readlane_b32 s14, v248, 5
	v_readlane_b32 s15, v248, 6
	s_cbranch_execz .LBB0_735
	s_load_dwordx4 s[4:7], s[90:91], 0xd0
	s_load_dwordx2 s[0:1], s[90:91], 0x0
	v_lshlrev_b32_e32 v0, 3, v218
	v_lshl_add_u32 v0, s2, 12, v0
	s_mov_b64 s[8:9], 0
	s_waitcnt lgkmcnt(0)
	s_add_u32 s2, s6, 0x15000000
	s_addc_u32 s3, s7, 0
	s_add_u32 s6, s6, 0x6000000
	s_addc_u32 s7, s7, 0
	s_lshl_b32 s10, s52, 12
	v_mov_b32_e32 v1, 0
	s_movk_i32 s11, 0x380
	v_mov_b32_e32 v3, 0x380
	v_mov_b32_e32 v4, 0x280
	s_movk_i32 s12, 0x17f
	s_mov_b32 s13, 0x3fffff
